# P7: LN1 gamma/beta hoisted out of the row loop and next row prefetched; expert-table loop prefetches the next row
# speedup vs baseline: 1.0135x; 1.0062x over previous
; DI float wave_sum(float v) { v = dpp_row_sum_f0(v); return (rl_f(v, 0) + rl_f(v, 16)) + (rl_f(v, 32) + rl_f(v, 48)); }
; DI void phase7(const Params& P, char* smem) {
;     ...
;   const int wid = VT >> 6, lane = VT & 63;
;   for (int row = VB * 4 + wid; row < NTOK; row += NVB * 4) {
;     float4 z[4]; float s = 0.f;
; #pragma unroll
;     for (int k = 0; k < 4; ++k) { z[k] = *reinterpret_cast<const float4*>(Z1 + (long)row * 1024 + k * 256 + lane * 4); s += z[k].x + z[k].y + z[k].z + z[k].w; }
;     const float mu = wave_sum(s) * (1.f / 1024.f);
;     float q = 0.f;
; #pragma unroll
;     for (int k = 0; k < 4; ++k) { float a = z[k].x - mu, b = z[k].y - mu, c = z[k].z - mu, d = z[k].w - mu; q += a * a + b * b + c * c + d * d; }
;     const float rstd = rsqrtf(wave_sum(q) * (1.f / 1024.f) + 1e-5f);
; #pragma unroll
;     for (int k = 0; k < 4; ++k) {
;       const int c0 = k * 256 + lane * 4;
;       const float4 gg = *reinterpret_cast<const float4*>(P.ln1g + c0), bb = *reinterpret_cast<const float4*>(P.ln1b + c0);
.LBB0_1001:
	s_or_b64 exec, exec, s[0:1]
	s_waitcnt lgkmcnt(0)
	v_and_b32_e32 v0, 12, v172
	v_lshl_add_u32 v0, s74, 3, v0
	v_or_b32_e32 v210, v0, v194
	s_mov_b32 s0, 0x8000
	v_ashrrev_i32_e32 v211, 31, v210
	s_barrier
	v_cmp_gt_i32_e64 s[0:1], s0, v210
	s_mov_b64 s[10:11], exec
	s_nop 0
	v_writelane_b32 v254, s0, 39
	s_nop 1
	v_writelane_b32 v254, s1, 40
	s_and_b64 s[0:1], s[10:11], s[0:1]
	s_mov_b64 exec, s[0:1]
	s_cbranch_execz .LBB0_1014
	v_readlane_b32 s16, v254, 16
	v_readlane_b32 s0, v254, 8
	v_readlane_b32 s17, v254, 17
	v_readlane_b32 s18, v254, 18
	v_readlane_b32 s19, v254, 19
	v_readlane_b32 s24, v254, 24
	v_readlane_b32 s25, v254, 25
	s_lshl_b32 s12, s0, 3
	v_mov_b32_e32 v0, 0
	v_readlane_b32 s26, v254, 26
	v_readlane_b32 s27, v254, 27
	s_mov_b64 s[16:17], s[24:25]
	v_lshlrev_b32_e32 v16, 4, v208
	v_mov_b32_e32 v17, v0
	v_readlane_b32 s20, v254, 20
	v_readlane_b32 s21, v254, 21
	v_readlane_b32 s22, v254, 22
	s_mov_b64 s[18:19], s[26:27]
	v_mov_b64_e32 v[6:7], 0x1b000000
	s_ashr_i32 s13, s12, 31
	v_lshlrev_b64 v[8:9], 11, v[210:211]
	v_lshlrev_b64 v[10:11], 10, v[210:211]
	v_lshlrev_b64 v[12:13], 12, v[210:211]
	v_cmp_eq_u32_e64 s[6:7], 0, v208
	v_lshl_add_u64 v[2:3], s[16:17], 0, v[16:17]
	v_lshl_add_u64 v[4:5], s[18:19], 0, v[16:17]
	v_lshl_add_u64 v[6:7], v[210:211], 2, v[6:7]
	s_lshl_b64 s[14:15], s[12:13], 2
	v_lshl_or_b32 v8, v208, 3, v8
	s_lshl_b64 s[16:17], s[12:13], 11
	v_lshl_or_b32 v10, v208, 2, v10
	s_lshl_b64 s[18:19], s[12:13], 10
	v_lshl_or_b32 v12, v208, 4, v12
	s_lshl_b64 s[24:25], s[12:13], 12
	s_mov_b64 s[20:21], 0
	v_mov_b32_e32 v17, 0x3727c5ac
	s_mov_b32 s2, 0x800000
	s_brev_b32 s4, 32
	s_brev_b32 s5, 8
	s_mov_b32 s8, 0x42fe0000
	s_mov_b32 s9, 0x40c0c00
	s_mov_b32 s13, 0x19000000
	s_movk_i32 s22, 0x7fff
	v_mov_b32_e32 v18, v210
	v_readlane_b32 s1, v254, 9
	v_readlane_b32 s23, v254, 23
	v_readlane_b32 s28, v254, 28
	v_readlane_b32 s29, v254, 29
	v_readlane_b32 s30, v254, 30
	v_readlane_b32 s31, v254, 31
	s_mov_b64 s[34:35], 0x8000000
	global_load_dwordx4 v[80:83], v[2:3], off
	global_load_dwordx4 v[84:87], v[2:3], off offset:1024
	global_load_dwordx4 v[88:91], v[2:3], off offset:2048
	global_load_dwordx4 v[92:95], v[2:3], off offset:3072
	global_load_dwordx4 v[96:99], v[4:5], off
	global_load_dwordx4 v[100:103], v[4:5], off offset:1024
	global_load_dwordx4 v[104:107], v[4:5], off offset:2048
	global_load_dwordx4 v[108:111], v[4:5], off offset:3072
	v_lshl_add_u64 v[130:131], s[78:79], 0, v[12:13]
	v_lshl_add_u64 v[130:131], v[130:131], 0, s[34:35]
	global_load_dwordx4 v[112:115], v[130:131], off offset:2048
	global_load_dwordx4 v[116:119], v[130:131], off offset:3072
	global_load_dwordx4 v[120:123], v[130:131], off
	global_load_dwordx4 v[124:127], v[130:131], off offset:1024
	s_waitcnt vmcnt(0)
	s_branch .LBB0_1004

; DI unsigned pack2bf(float a, float b) { const f2_t v = {a, b}; return __builtin_bit_cast(unsigned, __builtin_convertvector(v, bf2_t)); }
; DI float wave_sum(float v) { v = dpp_row_sum_f0(v); return (rl_f(v, 0) + rl_f(v, 16)) + (rl_f(v, 32) + rl_f(v, 48)); }
; DI void phase7(const Params& P, char* smem) {
;     ...
;   for (int row = VB * 4 + wid; row < NTOK; row += NVB * 4) {
;     float4 z[4]; float s = 0.f;
; #pragma unroll
;     for (int k = 0; k < 4; ++k) { z[k] = *reinterpret_cast<const float4*>(Z1 + (long)row * 1024 + k * 256 + lane * 4); s += z[k].x + z[k].y + z[k].z + z[k].w; }
;     const float mu = wave_sum(s) * (1.f / 1024.f);
;     float q = 0.f;
; #pragma unroll
;     for (int k = 0; k < 4; ++k) { float a = z[k].x - mu, b = z[k].y - mu, c = z[k].z - mu, d = z[k].w - mu; q += a * a + b * b + c * c + d * d; }
;     const float rstd = rsqrtf(wave_sum(q) * (1.f / 1024.f) + 1e-5f);
; #pragma unroll
;     for (int k = 0; k < 4; ++k) {
;       const int c0 = k * 256 + lane * 4;
;       const float4 gg = *reinterpret_cast<const float4*>(P.ln1g + c0), bb = *reinterpret_cast<const float4*>(P.ln1b + c0);
;       const float y0 = (z[k].x - mu) * rstd * gg.x + bb.x, y1 = (z[k].y - mu) * rstd * gg.y + bb.y, y2 = (z[k].z - mu) * rstd * gg.z + bb.z, y3 = (z[k].w - mu) * rstd * gg.w + bb.w;
;       typedef _Float16 h4 __attribute__((ext_vector_type(4)));
;       h4 hv; hv[0] = (_Float16)y0; hv[1] = (_Float16)y1; hv[2] = (_Float16)y2; hv[3] = (_Float16)y3;
;       *reinterpret_cast<h4*>(h1h + (long)row * 1024 + c0) = hv;
;       *reinterpret_cast<uint2*>(h1b + (long)row * 1024 + c0) = make_uint2(pack2bf(y0, y1), pack2bf(y2, y3));
;       z[k] = make_float4(y0, y1, y2, y3);
.LBB0_1004:
	s_waitcnt vmcnt(13)
	v_mov_b64_e32 v[20:21], v[112:113]
	v_mov_b64_e32 v[22:23], v[114:115]
	v_mov_b64_e32 v[24:25], v[116:117]
	v_mov_b64_e32 v[26:27], v[118:119]
	v_mov_b64_e32 v[28:29], v[120:121]
	v_mov_b64_e32 v[30:31], v[122:123]
	v_mov_b64_e32 v[32:33], v[124:125]
	v_mov_b64_e32 v[34:35], v[126:127]
	v_lshl_add_u64 v[130:131], v[12:13], 0, s[24:25]
	v_lshl_add_u64 v[130:131], s[78:79], 0, v[130:131]
	v_lshl_add_u64 v[130:131], v[130:131], 0, s[34:35]
	global_load_dwordx4 v[112:115], v[130:131], off offset:2048
	global_load_dwordx4 v[116:119], v[130:131], off offset:3072
	global_load_dwordx4 v[120:123], v[130:131], off
	global_load_dwordx4 v[124:127], v[130:131], off offset:1024
	v_lshl_add_u64 v[44:45], s[78:79], 0, v[8:9]
	v_add_co_u32_e32 v14, vcc, s4, v44
	v_mov_b32_e32 v46, v20
	v_mov_b32_e32 v47, v24
	v_mov_b32_e32 v48, v21
	v_mov_b32_e32 v49, v25
	v_mov_b32_e32 v54, v29
	v_mov_b32_e32 v50, v22
	v_mov_b32_e32 v51, v26
	v_mov_b32_e32 v53, v27
	v_mov_b32_e32 v60, v24
	v_mov_b32_e32 v61, v20
	v_mov_b32_e32 v20, v25
	v_mov_b32_e32 v24, v26
	v_mov_b32_e32 v25, v22
	v_mov_b32_e32 v22, v27
	v_pk_add_f32 v[26:27], v[46:47], v[48:49]
	v_pk_add_f32 v[46:47], v[28:29], v[54:55]
	v_mov_b32_e32 v56, v30
	v_mov_b32_e32 v57, v33
	v_mov_b32_e32 v47, v32
	v_pk_mov_b32 v[58:59], v[30:31], v[34:35] op_sel:[1,0]
	v_pk_add_f32 v[46:47], v[46:47], v[56:57]
	v_mov_b32_e32 v1, v35
	v_pk_add_f32 v[46:47], v[46:47], v[58:59]
	v_mov_b32_e32 v52, v23
	v_pk_add_f32 v[26:27], v[26:27], v[50:51]
	v_pk_add_f32 v[46:47], v[46:47], v[0:1]
	v_pk_add_f32 v[26:27], v[26:27], v[52:53]
	v_add_f32_e32 v1, v46, v47
	v_add_f32_e32 v1, v1, v26
	v_add_f32_e32 v1, v1, v27
	v_addc_co_u32_e32 v15, vcc, 0, v45, vcc
	s_nop 0
	v_add_f32_dpp v1, v1, v1 quad_perm:[1,0,3,2] row_mask:0xf bank_mask:0xf bound_ctrl:1
	s_nop 1
	v_add_f32_dpp v1, v1, v1 quad_perm:[2,3,0,1] row_mask:0xf bank_mask:0xf bound_ctrl:1
	s_nop 1
	v_add_f32_dpp v1, v1, v1 row_half_mirror row_mask:0xf bank_mask:0xf bound_ctrl:1
	s_nop 1
	v_add_f32_dpp v1, v1, v1 row_mirror row_mask:0xf bank_mask:0xf bound_ctrl:1
	s_nop 0
	v_readlane_b32 s23, v1, 16
	v_readlane_b32 s26, v1, 48
	v_readlane_b32 s0, v1, 0
	v_readlane_b32 s1, v1, 32
	v_mov_b32_e32 v26, s23
	v_mov_b32_e32 v27, s26
	v_pk_add_f32 v[26:27], s[0:1], v[26:27]
	s_nop 0
	v_add_f32_e32 v1, v26, v27
	v_mul_f32_e32 v26, 0x3a800000, v1
	v_pk_add_f32 v[28:29], v[28:29], v[26:27] op_sel_hi:[1,0] neg_lo:[0,1] neg_hi:[0,1]
	v_pk_add_f32 v[32:33], v[32:33], v[26:27] op_sel_hi:[1,0] neg_lo:[0,1] neg_hi:[0,1]
	v_pk_add_f32 v[30:31], v[30:31], v[26:27] op_sel_hi:[1,0] neg_lo:[0,1] neg_hi:[0,1]
	v_pk_add_f32 v[34:35], v[34:35], v[26:27] op_sel_hi:[1,0] neg_lo:[0,1] neg_hi:[0,1]
	v_pk_add_f32 v[48:49], v[20:21], v[26:27] op_sel_hi:[1,0] neg_lo:[0,1] neg_hi:[0,1]
	v_pk_add_f32 v[50:51], v[24:25], v[26:27] op_sel_hi:[1,0] neg_lo:[0,1] neg_hi:[0,1]
	v_pk_mul_f32 v[20:21], v[28:29], v[28:29]
	v_pk_mul_f32 v[24:25], v[32:33], v[32:33]
	v_pk_add_f32 v[46:47], v[60:61], v[26:27] op_sel_hi:[1,0] neg_lo:[0,1] neg_hi:[0,1]
	v_pk_add_f32 v[52:53], v[22:23], v[26:27] op_sel_hi:[1,0] neg_lo:[0,1] neg_hi:[0,1]
	v_pk_mul_f32 v[22:23], v[30:31], v[30:31]
	v_pk_mul_f32 v[26:27], v[34:35], v[34:35]
	v_mov_b32_e32 v56, v20
	v_mov_b32_e32 v57, v24
	v_mov_b32_e32 v24, v21
	v_pk_mul_f32 v[54:55], v[48:49], v[48:49]
	v_mov_b32_e32 v20, v22
	v_mov_b32_e32 v21, v26
	v_pk_add_f32 v[24:25], v[56:57], v[24:25]
	v_mov_b32_e32 v26, v23
	v_pk_fma_f32 v[22:23], v[46:47], v[46:47], v[54:55]
	v_pk_add_f32 v[20:21], v[20:21], v[24:25]
	v_pk_fma_f32 v[22:23], v[50:51], v[50:51], v[22:23]
	v_pk_add_f32 v[20:21], v[26:27], v[20:21]
	v_pk_fma_f32 v[22:23], v[52:53], v[52:53], v[22:23]
	v_add_f32_e32 v1, v20, v21
	v_add_f32_e32 v1, v23, v1
	v_add_f32_e32 v1, v22, v1
	s_nop 1
	v_add_f32_dpp v1, v1, v1 quad_perm:[1,0,3,2] row_mask:0xf bank_mask:0xf bound_ctrl:1
	s_nop 1
	v_add_f32_dpp v1, v1, v1 quad_perm:[2,3,0,1] row_mask:0xf bank_mask:0xf bound_ctrl:1
	s_nop 1
	v_add_f32_dpp v1, v1, v1 row_half_mirror row_mask:0xf bank_mask:0xf bound_ctrl:1
	s_nop 1
	v_add_f32_dpp v1, v1, v1 row_mirror row_mask:0xf bank_mask:0xf bound_ctrl:1
	s_nop 0
	v_readlane_b32 s23, v1, 16
	v_readlane_b32 s26, v1, 48
	v_readlane_b32 s0, v1, 0
	v_readlane_b32 s1, v1, 32
	v_mov_b32_e32 v20, s23
	v_mov_b32_e32 v21, s26
	v_pk_add_f32 v[20:21], s[0:1], v[20:21]
	v_add_co_u32_e64 v44, s[0:1], s5, v44
	v_add_f32_e32 v1, v20, v21
	v_fmamk_f32 v1, v1, 0x3a800000, v17
	v_mul_f32_e32 v19, 0x4b800000, v1
	v_cmp_gt_f32_e32 vcc, s2, v1
	v_addc_co_u32_e64 v45, s[0:1], 0, v45, s[0:1]
	s_nop 0
	v_cndmask_b32_e32 v1, v1, v19, vcc
	v_rsq_f32_e32 v1, v1
	s_nop 0
	v_mul_f32_e32 v19, 0x45800000, v1
	v_cndmask_b32_e32 v54, v1, v19, vcc
	v_pk_mul_f32 v[20:21], v[28:29], v[54:55] op_sel_hi:[1,0]
	v_pk_mul_f32 v[22:23], v[30:31], v[54:55] op_sel_hi:[1,0]
	v_pk_fma_f32 v[28:29], v[80:81], v[20:21], v[96:97]
	v_pk_fma_f32 v[30:31], v[82:83], v[22:23], v[98:99]
	v_cvt_pk_f16_f32 v20, v28, v29
	v_cvt_pk_f16_f32 v21, v30, v31
	v_cvt_pk_bf16_f32 v22, v28, v29
	v_cvt_pk_bf16_f32 v23, v30, v31
	global_store_dwordx2 v[14:15], v[20:21], off
	global_store_dwordx2 v[44:45], v[22:23], off
	v_pk_mul_f32 v[32:33], v[32:33], v[54:55] op_sel_hi:[1,0]
	v_pk_mul_f32 v[34:35], v[34:35], v[54:55] op_sel_hi:[1,0]
	v_mov_b32_e32 v36, v47
	v_mov_b32_e32 v37, v49
	v_mov_b32_e32 v38, v51
	v_mov_b32_e32 v39, v53
	v_pk_mul_f32 v[36:37], v[36:37], v[54:55] op_sel_hi:[1,0]
	v_pk_mul_f32 v[38:39], v[38:39], v[54:55] op_sel_hi:[1,0]
	v_mov_b32_e32 v47, v48
	v_mov_b32_e32 v51, v52
	v_pk_mul_f32 v[42:43], v[46:47], v[54:55] op_sel_hi:[1,0]
	v_pk_mul_f32 v[46:47], v[50:51], v[54:55] op_sel_hi:[1,0]
; DI unsigned pack2bf(float a, float b) { const f2_t v = {a, b}; return __builtin_bit_cast(unsigned, __builtin_convertvector(v, bf2_t)); }
; DI void phase7(const Params& P, char* smem) {
;     ...
;     for (int k = 0; k < 4; ++k) {
;       const int c0 = k * 256 + lane * 4;
;       const float4 gg = *reinterpret_cast<const float4*>(P.ln1g + c0), bb = *reinterpret_cast<const float4*>(P.ln1b + c0);
;       const float y0 = (z[k].x - mu) * rstd * gg.x + bb.x, y1 = (z[k].y - mu) * rstd * gg.y + bb.y, y2 = (z[k].z - mu) * rstd * gg.z + bb.z, y3 = (z[k].w - mu) * rstd * gg.w + bb.w;
;       typedef _Float16 h4 __attribute__((ext_vector_type(4)));
;       h4 hv; hv[0] = (_Float16)y0; hv[1] = (_Float16)y1; hv[2] = (_Float16)y2; hv[3] = (_Float16)y3;
;       *reinterpret_cast<h4*>(h1h + (long)row * 1024 + c0) = hv;
;       *reinterpret_cast<uint2*>(h1b + (long)row * 1024 + c0) = make_uint2(pack2bf(y0, y1), pack2bf(y2, y3));
;       z[k] = make_float4(y0, y1, y2, y3);
;     }
;     float am = 0.f;
; #pragma unroll
;     for (int k = 0; k < 4; ++k) am = fmaxf(am, fmaxf(fmaxf(fabsf(z[k].x), fabsf(z[k].y)), fmaxf(fabsf(z[k].z), fabsf(z[k].w))));
;     am = wave_max(am);
;     const float xinv = am > 0.f ? 127.f / am : 0.f;
; #pragma unroll
;     for (int k = 0; k < 4; ++k) {
;       const unsigned pk = ((unsigned)((int)rintf(z[k].x * xinv) & 0xff)) | ((unsigned)((int)rintf(z[k].y * xinv) & 0xff) << 8) |
;                           ((unsigned)((int)rintf(z[k].z * xinv) & 0xff) << 16) | ((unsigned)((int)rintf(z[k].w * xinv) & 0xff) << 24);
;       *reinterpret_cast<unsigned*>(ws + OFF_XQ + (long)row * 1024 + k * 256 + lane * 4) = pk;
;     }
;     if (lane == 0) reinterpret_cast<float*>(ws + OFF_SX)[row] = am * (1.f / 127.f);
;     ...
;   for (int row = VB * 4 + wid; row < 2 * 16384; row += NVB * 4) {
;     const bool isv = row >= 16384; const int e = row & 16383;
;     const float* src = (isv ? P.pv : P.pu) + (long)e * 1024 + lane * 16;
;     float f[16];
; #pragma unroll
;     for (int k = 0; k < 4; ++k) { const float4 a = reinterpret_cast<const float4*>(src)[k]; f[4 * k] = a.x; f[4 * k + 1] = a.y; f[4 * k + 2] = a.z; f[4 * k + 3] = a.w; }
	v_max_f32_e64 v1, |v30|, |v31|
	v_max3_f32 v1, |v28|, |v29|, v1
	v_lshl_add_u64 v[40:41], s[78:79], 0, v[10:11]
	v_add_co_u32_e32 v40, vcc, s13, v40
	v_pk_fma_f32 v[32:33], v[32:33], v[84:85], v[100:101]
	v_pk_fma_f32 v[34:35], v[34:35], v[86:87], v[102:103]
	v_cvt_pk_f16_f32 v20, v32, v33
	v_cvt_pk_f16_f32 v21, v34, v35
	v_cvt_pk_bf16_f32 v22, v32, v33
	v_cvt_pk_bf16_f32 v23, v34, v35
	global_store_dwordx2 v[14:15], v[20:21], off offset:512
	global_store_dwordx2 v[44:45], v[22:23], off offset:512
	v_max_f32_e64 v19, |v34|, |v35|
	v_max3_f32 v19, |v32|, |v33|, v19
	v_max3_f32 v1, v1, 0, v19
	v_addc_co_u32_e32 v41, vcc, 0, v41, vcc
	v_pk_fma_f32 v[36:37], v[36:37], v[88:89], v[104:105]
	v_pk_fma_f32 v[38:39], v[38:39], v[90:91], v[106:107]
	v_cvt_pk_f16_f32 v20, v36, v37
	v_cvt_pk_f16_f32 v21, v38, v39
	v_cvt_pk_bf16_f32 v22, v36, v37
	v_cvt_pk_bf16_f32 v23, v38, v39
	global_store_dwordx2 v[14:15], v[20:21], off offset:1024
	global_store_dwordx2 v[44:45], v[22:23], off offset:1024
	v_max_f32_e64 v19, |v38|, |v39|
	v_max3_f32 v19, |v36|, |v37|, v19
	v_pk_fma_f32 v[20:21], v[42:43], v[92:93], v[108:109]
	v_pk_fma_f32 v[22:23], v[46:47], v[94:95], v[110:111]
	v_cvt_pk_f16_f32 v24, v20, v21
	v_cvt_pk_f16_f32 v25, v22, v23
	v_max_f32_e64 v42, |v22|, |v23|
	global_store_dwordx2 v[14:15], v[24:25], off offset:1536
	v_max3_f32 v14, |v20|, |v21|, v42
	v_max3_f32 v1, v1, v19, v14
	v_cvt_pk_bf16_f32 v26, v20, v21
	v_cvt_pk_bf16_f32 v27, v22, v23
	v_mov_b32_dpp v14, v1 quad_perm:[1,0,3,2] row_mask:0xf bank_mask:0xf bound_ctrl:1
	v_max_f32_e32 v14, v14, v14
	v_max_f32_e32 v1, v1, v14
	global_store_dwordx2 v[44:45], v[26:27], off offset:1536
	s_nop 0
	v_mov_b32_dpp v14, v1 quad_perm:[2,3,0,1] row_mask:0xf bank_mask:0xf bound_ctrl:1
	v_max_f32_e32 v14, v14, v14
	v_max_f32_e32 v1, v1, v14
	s_nop 1
	v_mov_b32_dpp v14, v1 row_half_mirror row_mask:0xf bank_mask:0xf bound_ctrl:1
	v_max_f32_e32 v14, v14, v14
	v_max_f32_e32 v1, v1, v14
	s_nop 1
	v_mov_b32_dpp v14, v1 row_mirror row_mask:0xf bank_mask:0xf bound_ctrl:1
	v_max_f32_e32 v14, v14, v14
	v_max_f32_e32 v1, v1, v14
	s_nop 0
	v_readlane_b32 s23, v1, 32
	v_readlane_b32 s26, v1, 48
	v_readlane_b32 s0, v1, 0
	v_readlane_b32 s1, v1, 16
	v_max_f32_e64 v1, s26, s26
	v_max_f32_e64 v14, s23, s23
	v_mov_b32_e32 v15, s1
	v_max_f32_e32 v1, v14, v1
	v_max3_f32 v1, s0, v15, v1
	v_div_scale_f32 v14, s[0:1], v1, v1, s8
	v_rcp_f32_e32 v15, v14
	v_div_scale_f32 v19, vcc, s8, v1, s8
	v_fma_f32 v24, -v14, v15, 1.0
	v_fmac_f32_e32 v15, v24, v15
	v_mul_f32_e32 v24, v19, v15
	v_fma_f32 v25, -v14, v24, v19
	v_fmac_f32_e32 v24, v25, v15
	v_fma_f32 v14, -v14, v24, v19
	v_div_fmas_f32 v14, v14, v15, v24
	v_div_fixup_f32 v14, v14, v1, s8
	v_cmp_lt_f32_e32 vcc, 0, v1
	s_nop 1
	v_cndmask_b32_e32 v14, 0, v14, vcc
	v_mul_f32_e32 v19, v29, v14
	v_mul_f32_e32 v15, v28, v14
	v_mul_f32_e32 v24, v30, v14
	v_mul_f32_e32 v25, v31, v14
	v_mul_f32_e32 v26, v32, v14
	v_mul_f32_e32 v27, v33, v14
	v_mul_f32_e32 v28, v34, v14
	v_mul_f32_e32 v29, v35, v14
	v_mul_f32_e32 v30, v36, v14
	v_mul_f32_e32 v31, v37, v14
	v_mul_f32_e32 v21, v21, v14
	v_rndne_f32_e32 v19, v19
	v_mul_f32_e32 v32, v38, v14
	v_mul_f32_e32 v33, v39, v14
	v_mul_f32_e32 v20, v20, v14
	v_mul_f32_e32 v22, v22, v14
	v_mul_f32_e32 v14, v23, v14
	v_rndne_f32_e32 v15, v15
	v_rndne_f32_e32 v23, v24
	v_rndne_f32_e32 v24, v25
	v_rndne_f32_e32 v25, v26
	v_rndne_f32_e32 v26, v27
	v_rndne_f32_e32 v27, v28
	v_rndne_f32_e32 v28, v29
	v_rndne_f32_e32 v29, v30
	v_rndne_f32_e32 v30, v31
	v_rndne_f32_e32 v21, v21
	v_cvt_i32_f32_e32 v19, v19
	v_rndne_f32_e32 v31, v32
	v_rndne_f32_e32 v32, v33
	v_rndne_f32_e32 v20, v20
	v_rndne_f32_e32 v22, v22
	v_rndne_f32_e32 v14, v14
	v_cvt_i32_f32_e32 v15, v15
	v_cvt_i32_f32_sdwa v23, v23 dst_sel:WORD_1 dst_unused:UNUSED_PAD src0_sel:DWORD
	v_cvt_i32_f32_e32 v24, v24
	v_cvt_i32_f32_e32 v26, v26
	v_cvt_i32_f32_sdwa v27, v27 dst_sel:WORD_1 dst_unused:UNUSED_PAD src0_sel:DWORD
	v_cvt_i32_f32_e32 v30, v30
	v_cvt_i32_f32_e32 v21, v21
	v_cvt_i32_f32_e32 v25, v25
	v_cvt_i32_f32_e32 v28, v28
	v_cvt_i32_f32_e32 v29, v29
	v_cvt_i32_f32_sdwa v31, v31 dst_sel:WORD_1 dst_unused:UNUSED_PAD src0_sel:DWORD
	v_cvt_i32_f32_e32 v32, v32
	v_cvt_i32_f32_e32 v20, v20
	v_cvt_i32_f32_sdwa v22, v22 dst_sel:WORD_1 dst_unused:UNUSED_PAD src0_sel:DWORD
	v_cvt_i32_f32_e32 v14, v14
	v_lshlrev_b32_e32 v19, 8, v19
	v_and_b32_e32 v23, 0xff0000, v23
	v_perm_b32 v15, v24, v15, s9
	v_lshlrev_b32_e32 v24, 8, v26
	v_and_b32_e32 v26, 0xff0000, v27
	v_lshlrev_b32_e32 v27, 8, v30
	v_lshlrev_b32_e32 v21, 8, v21
	v_and_b32_e32 v19, 0xff00, v19
	v_perm_b32 v25, v28, v25, s9
	v_and_b32_e32 v28, 0xff0000, v31
	v_perm_b32 v29, v32, v29, s9
	v_and_b32_e32 v22, 0xff0000, v22
	v_perm_b32 v14, v14, v20, s9
	v_and_b32_e32 v20, 0xff00, v24
	v_and_b32_e32 v24, 0xff00, v27
	v_and_b32_e32 v21, 0xff00, v21
	v_or3_b32 v15, v15, v19, v23
	v_or3_b32 v19, v25, v20, v26
	v_or3_b32 v20, v29, v24, v28
	v_or3_b32 v14, v14, v21, v22
	global_store_dword v[40:41], v15, off
	global_store_dword v[40:41], v19, off offset:256
	global_store_dword v[40:41], v20, off offset:512
	global_store_dword v[40:41], v14, off offset:768
	s_and_saveexec_b64 s[0:1], s[6:7]
	s_cbranch_execz .LBB0_1003
	v_mul_f32_e32 v1, 0x3c010204, v1
	v_lshl_add_u64 v[14:15], s[78:79], 0, v[6:7]
	global_store_dword v[14:15], v1, off
	s_branch .LBB0_1003
.LBB0_1006:
	s_or_b64 exec, exec, s[20:21]
	v_lshlrev_b32_e32 v0, 11, v189
	v_readlane_b32 s16, v254, 0
	v_mov_b32_e32 v19, 0
	v_and_b32_e32 v17, 0x1c000, v0
	v_and_b32_e32 v0, 0x70, v209
	v_readlane_b32 s17, v254, 1
	v_readlane_b32 s18, v254, 2
	v_readlane_b32 s19, v254, 3
	v_or_b32_e32 v24, 0x1000000, v0
	s_mov_b64 s[14:15], 0
	s_movk_i32 s2, 0x4000
	s_movk_i32 s4, 0x3fff
	v_mov_b32_e32 v25, s17
	v_mov_b32_e32 v26, s19
	v_mov_b32_e32 v27, s16
	v_mov_b32_e32 v28, s18
	v_lshlrev_b32_e32 v20, 2, v16
	v_mov_b32_e32 v21, v19
	s_mov_b32 s5, 0x42fe0000
	s_movk_i32 s13, 0xff81
	s_movk_i32 s16, 0xff
	s_movk_i32 s17, 0x7fff
	v_mov_b32_e32 v29, 0x7f
	v_mov_b32_e32 v30, v210
	v_readlane_b32 s20, v254, 4
	v_readlane_b32 s21, v254, 5
	v_readlane_b32 s22, v254, 6
	v_readlane_b32 s23, v254, 7
	v_mov_b32_e32 v148, v30
	v_and_b32_e32 v149, 0x3fff, v148
	v_cmp_lt_i32_e64 s[32:33], s4, v148
	v_lshlrev_b32_e32 v150, 12, v149
	v_mov_b32_e32 v151, 0
	s_nop 0
	v_cndmask_b32_e64 v153, v25, v26, s[32:33]
	v_cndmask_b32_e64 v152, v27, v28, s[32:33]
	v_lshl_add_u64 v[152:153], v[152:153], 0, v[150:151]
	v_lshl_add_u64 v[152:153], v[152:153], 0, v[20:21]
	global_load_dwordx4 v[132:135], v[152:153], off
	global_load_dwordx4 v[136:139], v[152:153], off offset:16
	global_load_dwordx4 v[140:143], v[152:153], off offset:32
	global_load_dwordx4 v[144:147], v[152:153], off offset:48
	s_waitcnt vmcnt(0)
	s_branch .LBB0_1008

; DI void phase7(const Params& P, char* smem) {
;     ...
;   for (int row = VB * 4 + wid; row < 2 * 16384; row += NVB * 4) {
;     const bool isv = row >= 16384; const int e = row & 16383;
;     const float* src = (isv ? P.pv : P.pu) + (long)e * 1024 + lane * 16;
;     float f[16];
; #pragma unroll
;     for (int k = 0; k < 4; ++k) { const float4 a = reinterpret_cast<const float4*>(src)[k]; f[4 * k] = a.x; f[4 * k + 1] = a.y; f[4 * k + 2] = a.z; f[4 * k + 3] = a.w; }
;     float am = 0.f;
; #pragma unroll
;     for (int k = 0; k < 16; ++k) am = fmaxf(am, fabsf(f[k]));
;     am = wave_max(am);
;     const float inv = am > 0.f ? 127.f / am : 0.f;
;     unsigned w[4];
; #pragma unroll
;     for (int k = 0; k < 4; ++k) {
;       unsigned pk = 0;
; #pragma unroll
;       for (int b = 0; b < 4; ++b) { int q = (int)rintf(f[4 * k + b] * inv); q = q > 127 ? 127 : (q < -127 ? -127 : q); pk |= ((unsigned)((isv ? q + 128 : q) & 0xff)) << (8 * b); }
;       w[k] = pk;
;     }
;     *reinterpret_cast<uint4*>(ws + (isv ? OFF_VQ + ((long)(lane >> 3) * 16384 + e) * 128 + (lane & 7) * 16 : OFF_UQ + (long)e * 1024 + lane * 16)) = make_uint4(w[0], w[1], w[2], w[3]);
;     if (lane == 0) reinterpret_cast<float*>(ws + (isv ? OFF_VS : OFF_US))[e] = am * (1.f / 127.f);
;   }
.LBB0_1008:
	s_waitcnt vmcnt(2)
	v_mov_b64_e32 v[12:13], v[132:133]
	v_mov_b64_e32 v[14:15], v[134:135]
	v_mov_b64_e32 v[8:9], v[136:137]
	v_mov_b64_e32 v[10:11], v[138:139]
	v_mov_b64_e32 v[4:5], v[140:141]
	v_mov_b64_e32 v[6:7], v[142:143]
	v_mov_b64_e32 v[0:1], v[144:145]
	v_mov_b64_e32 v[2:3], v[146:147]
	v_add_u32_e32 v148, s12, v30
	v_and_b32_e32 v149, 0x3fff, v148
	v_cmp_lt_i32_e64 s[32:33], s4, v148
	v_lshlrev_b32_e32 v150, 12, v149
	v_mov_b32_e32 v151, 0
	s_nop 0
	v_cndmask_b32_e64 v153, v25, v26, s[32:33]
	v_cndmask_b32_e64 v152, v27, v28, s[32:33]
	v_lshl_add_u64 v[152:153], v[152:153], 0, v[150:151]
	v_lshl_add_u64 v[152:153], v[152:153], 0, v[20:21]
	global_load_dwordx4 v[132:135], v[152:153], off
	global_load_dwordx4 v[136:139], v[152:153], off offset:16
	global_load_dwordx4 v[140:143], v[152:153], off offset:32
	global_load_dwordx4 v[144:147], v[152:153], off offset:48
	v_and_b32_e32 v31, 0x3fff, v30
	v_cmp_lt_i32_e64 s[0:1], s4, v30
	v_cmp_gt_i32_e32 vcc, s2, v30
	v_max3_f32 v18, |v12|, 0, |v13|
	v_max3_f32 v18, v18, |v14|, |v15|
	v_max3_f32 v18, v18, |v8|, |v9|
	v_max3_f32 v18, v18, |v10|, |v11|
	v_max3_f32 v18, v18, |v4|, |v5|
	v_max3_f32 v18, v18, |v6|, |v7|
	v_max3_f32 v18, v18, |v0|, |v1|
	v_max3_f32 v18, v18, |v2|, |v3|
	s_nop 1
	v_mov_b32_dpp v22, v18 quad_perm:[1,0,3,2] row_mask:0xf bank_mask:0xf bound_ctrl:1
	v_max_f32_e32 v22, v22, v22
	v_max_f32_e32 v18, v18, v22
	s_nop 1
	v_mov_b32_dpp v22, v18 quad_perm:[2,3,0,1] row_mask:0xf bank_mask:0xf bound_ctrl:1
	v_max_f32_e32 v22, v22, v22
	v_max_f32_e32 v18, v18, v22
	s_nop 1
	v_mov_b32_dpp v22, v18 row_half_mirror row_mask:0xf bank_mask:0xf bound_ctrl:1
	v_max_f32_e32 v22, v22, v22
	v_max_f32_e32 v18, v18, v22
	s_nop 1
	v_mov_b32_dpp v22, v18 row_mirror row_mask:0xf bank_mask:0xf bound_ctrl:1
	v_max_f32_e32 v22, v22, v22
	v_max_f32_e32 v18, v18, v22
	s_nop 0
	v_readlane_b32 s18, v18, 0
	v_readlane_b32 s19, v18, 16
	v_readlane_b32 s20, v18, 32
	v_readlane_b32 s21, v18, 48
	s_and_saveexec_b64 s[8:9], vcc
	s_xor_b64 s[8:9], exec, s[8:9]
	v_lshlrev_b32_e32 v18, 10, v31
	v_or_b32_e32 v18, v18, v16
	s_or_saveexec_b64 s[8:9], s[8:9]
	v_mov_b64_e32 v[22:23], 0x2000000
	s_xor_b64 exec, exec, s[8:9]
	v_or_b32_e32 v18, v31, v17
	v_lshl_or_b32 v18, v18, 7, v24
	v_mov_b64_e32 v[22:23], 0x2100000
	s_or_b64 exec, exec, s[8:9]
	v_max_f32_e64 v32, s21, s21
	v_max_f32_e64 v33, s20, s20
	v_max_f32_e32 v32, v33, v32
	v_mov_b32_e32 v33, s19
	v_max3_f32 v32, s18, v33, v32
	v_div_scale_f32 v33, s[8:9], v32, v32, s5
	v_rcp_f32_e32 v34, v33
	s_nop 0
	v_fma_f32 v35, -v33, v34, 1.0
	v_fmac_f32_e32 v34, v35, v34
	v_div_scale_f32 v35, vcc, s5, v32, s5
	v_mul_f32_e32 v36, v35, v34
	v_fma_f32 v37, -v33, v36, v35
	v_fmac_f32_e32 v36, v37, v34
	v_fma_f32 v33, -v33, v36, v35
	v_div_fmas_f32 v33, v33, v34, v36
	v_div_fixup_f32 v33, v33, v32, s5
	v_cmp_lt_f32_e32 vcc, 0, v32
	s_nop 1
	v_cndmask_b32_e32 v33, 0, v33, vcc
	v_mul_f32_e32 v12, v12, v33
	v_mul_f32_e32 v13, v13, v33
	v_rndne_f32_e32 v12, v12
	v_rndne_f32_e32 v13, v13
	v_mul_f32_e32 v14, v14, v33
	v_cvt_i32_f32_e32 v12, v12
	v_cvt_i32_f32_e32 v13, v13
	v_rndne_f32_e32 v14, v14
	v_mul_f32_e32 v15, v15, v33
	v_cvt_i32_f32_e32 v14, v14
	v_rndne_f32_e32 v15, v15
	v_cvt_i32_f32_e32 v15, v15
	v_mul_f32_e32 v8, v8, v33
	v_mul_f32_e32 v9, v9, v33
	v_med3_i32 v12, v12, s13, v29
	v_med3_i32 v13, v13, s13, v29
	v_rndne_f32_e32 v8, v8
	v_rndne_f32_e32 v9, v9
	v_mul_f32_e32 v10, v10, v33
	v_xor_b32_e32 v34, 0x80, v12
	v_lshlrev_b32_e32 v13, 8, v13
	v_med3_i32 v14, v14, s13, v29
	v_cvt_i32_f32_e32 v8, v8
	v_cvt_i32_f32_e32 v9, v9
	v_rndne_f32_e32 v10, v10
	v_mul_f32_e32 v11, v11, v33
	v_cndmask_b32_e64 v12, v12, v34, s[0:1]
	v_xor_b32_e32 v34, 0x8000, v13
	v_lshlrev_b32_e32 v14, 16, v14
	v_med3_i32 v15, v15, s13, v29
	v_cvt_i32_f32_e32 v10, v10
	v_rndne_f32_e32 v11, v11
	v_cndmask_b32_e64 v13, v13, v34, s[0:1]
	v_xor_b32_e32 v34, 0x800000, v14
	v_lshlrev_b32_e32 v15, 24, v15
	v_cvt_i32_f32_e32 v11, v11
	v_cndmask_b32_e64 v14, v14, v34, s[0:1]
	v_cndmask_b32_e64 v15, v15, -v15, s[0:1]
	v_mul_f32_e32 v4, v4, v33
	v_mul_f32_e32 v5, v5, v33
	v_and_b32_e32 v13, 0xff00, v13
	v_and_b32_e32 v14, 0xff0000, v14
	v_and_or_b32 v12, v12, s16, v15
	v_med3_i32 v8, v8, s13, v29
	v_med3_i32 v9, v9, s13, v29
	v_rndne_f32_e32 v4, v4
	v_rndne_f32_e32 v5, v5
	v_mul_f32_e32 v6, v6, v33
	v_or3_b32 v12, v12, v13, v14
	v_xor_b32_e32 v13, 0x80, v8
	v_lshlrev_b32_e32 v9, 8, v9
	v_med3_i32 v10, v10, s13, v29
	v_cvt_i32_f32_e32 v4, v4
	v_cvt_i32_f32_e32 v5, v5
	v_rndne_f32_e32 v6, v6
	v_mul_f32_e32 v7, v7, v33
	v_cndmask_b32_e64 v8, v8, v13, s[0:1]
	v_xor_b32_e32 v13, 0x8000, v9
	v_lshlrev_b32_e32 v10, 16, v10
	v_med3_i32 v11, v11, s13, v29
	v_cvt_i32_f32_e32 v6, v6
	v_rndne_f32_e32 v7, v7
	v_cndmask_b32_e64 v9, v9, v13, s[0:1]
	v_xor_b32_e32 v13, 0x800000, v10
	v_lshlrev_b32_e32 v11, 24, v11
	v_cvt_i32_f32_e32 v7, v7
	v_cndmask_b32_e64 v10, v10, v13, s[0:1]
	v_cndmask_b32_e64 v11, v11, -v11, s[0:1]
	v_mul_f32_e32 v0, v0, v33
	v_mul_f32_e32 v1, v1, v33
	v_and_b32_e32 v9, 0xff00, v9
	v_and_b32_e32 v10, 0xff0000, v10
	v_and_or_b32 v8, v8, s16, v11
	v_med3_i32 v4, v4, s13, v29
	v_med3_i32 v5, v5, s13, v29
	v_rndne_f32_e32 v0, v0
	v_rndne_f32_e32 v1, v1
	v_mul_f32_e32 v2, v2, v33
	v_or3_b32 v13, v8, v9, v10
	v_xor_b32_e32 v8, 0x80, v4
	v_lshlrev_b32_e32 v5, 8, v5
	v_med3_i32 v6, v6, s13, v29
	v_cvt_i32_f32_e32 v0, v0
	v_cvt_i32_f32_e32 v1, v1
	v_rndne_f32_e32 v2, v2
	v_mul_f32_e32 v3, v3, v33
	v_cndmask_b32_e64 v4, v4, v8, s[0:1]
	v_xor_b32_e32 v8, 0x8000, v5
	v_lshlrev_b32_e32 v6, 16, v6
	v_med3_i32 v7, v7, s13, v29
	v_cvt_i32_f32_e32 v2, v2
	v_rndne_f32_e32 v3, v3
	v_cndmask_b32_e64 v5, v5, v8, s[0:1]
	v_xor_b32_e32 v8, 0x800000, v6
	v_lshlrev_b32_e32 v7, 24, v7
	v_cvt_i32_f32_e32 v3, v3
	v_cndmask_b32_e64 v6, v6, v8, s[0:1]
	v_cndmask_b32_e64 v7, v7, -v7, s[0:1]
	v_and_b32_e32 v5, 0xff00, v5
	v_and_b32_e32 v6, 0xff0000, v6
	v_and_or_b32 v4, v4, s16, v7
	v_med3_i32 v0, v0, s13, v29
	v_med3_i32 v1, v1, s13, v29
	v_or3_b32 v14, v4, v5, v6
	v_xor_b32_e32 v4, 0x80, v0
	v_lshlrev_b32_e32 v1, 8, v1
	v_med3_i32 v2, v2, s13, v29
	v_cndmask_b32_e64 v0, v0, v4, s[0:1]
	v_xor_b32_e32 v4, 0x8000, v1
	v_lshlrev_b32_e32 v2, 16, v2
	v_med3_i32 v3, v3, s13, v29
	v_cndmask_b32_e64 v1, v1, v4, s[0:1]
	v_xor_b32_e32 v4, 0x800000, v2
	v_lshlrev_b32_e32 v3, 24, v3
	v_cndmask_b32_e64 v2, v2, v4, s[0:1]
	v_cndmask_b32_e64 v3, v3, -v3, s[0:1]
	v_and_b32_e32 v1, 0xff00, v1
	v_and_b32_e32 v2, 0xff0000, v2
	v_and_or_b32 v0, v0, s16, v3
	v_or3_b32 v15, v0, v1, v2
	v_lshl_add_u64 v[0:1], s[78:79], 0, v[18:19]
	global_store_dwordx4 v[0:1], v[12:15], off
	s_and_saveexec_b64 s[0:1], s[6:7]
	s_cbranch_execz .LBB0_1007
	v_lshl_add_u64 v[0:1], s[78:79], 0, v[22:23]
	v_lshlrev_b32_e32 v18, 2, v31
	v_mul_f32_e32 v2, 0x3c010204, v32
	v_lshl_add_u64 v[0:1], v[0:1], 0, v[18:19]
	global_store_dword v[0:1], v2, off
	s_branch .LBB0_1007
